# seam after the setup phase uses the XCD-hierarchical barrier (same release/acquire fences) instead of the cooperative-groups grid sync; ph_qkv Q stage_tile batched rs reads
# speedup vs baseline: 1.0068x; 1.0033x over previous
; DI int tid() { int t = threadIdx.x; asm volatile("" : "+v"(t)); return t; }
; DI int crow(int r, int h) { return (r & 3) + 8 * (r >> 2) + 4 * h; }
; DI float* stage_tile(const f32x16 (&acc)[2][2], const float* rs, char* smem) {
;     const int tt = tid(), lane = tt & 63, w = __builtin_amdgcn_readfirstlane(tt >> 6), wm = w >> 1, wn = w & 1, l32 = lane & 31, h = lane >> 5;
;     float* stg = (float*)smem;
; #pragma unroll
;     for (int i = 0; i < 2; ++i)
; #pragma unroll
;         for (int j = 0; j < 2; ++j)
; #pragma unroll
;             for (int r = 0; r < 16; ++r) {
;                 const int row = wm * 64 + i * 32 + crow(r, h);
;                 stg[row * 132 + wn * 64 + j * 32 + l32] = rs ? acc[i][j][r] * rs[row] : acc[i][j][r];
;             }
;     __syncthreads();
;     return stg;
.LBB0_212:
	s_or_b64 exec, exec, s[16:17]
	v_mov_b32_e32 v32, v182
	s_waitcnt lgkmcnt(0)
	s_barrier
	s_nop 0
	v_readfirstlane_b32 s9, v32
	s_ashr_i32 s8, s9, 1
	v_lshrrev_b32_e32 v33, 3, v32
	s_and_b32 s10, s8, 0xffffffc0
	v_and_b32_e32 v33, 4, v33
	v_or_b32_e32 v34, s10, v33
	s_add_i32 s8, 0, 0x12000
	v_lshl_add_u32 v68, v34, 2, s8
	v_and_b32_e32 v32, 31, v32
	v_and_or_b32 v32, s9, 64, v32
	v_mul_lo_u32 v34, v34, s82
	v_lshlrev_b32_e32 v32, 2, v32
	v_add3_u32 v34, 0, v34, v32
	ds_read_b128 v[70:73], v68
	ds_read_b128 v[74:77], v68 offset:32
	ds_read_b128 v[78:81], v68 offset:64
	ds_read_b128 v[82:85], v68 offset:96
	s_waitcnt lgkmcnt(0)
	v_mul_f32_e32 v52, v52, v70
	v_mul_f32_e32 v53, v53, v71
	v_mul_f32_e32 v54, v54, v72
	v_mul_f32_e32 v55, v55, v73
	v_mul_f32_e32 v56, v56, v74
	v_mul_f32_e32 v57, v57, v75
	v_mul_f32_e32 v58, v58, v76
	v_mul_f32_e32 v59, v59, v77
	v_mul_f32_e32 v60, v60, v78
	v_mul_f32_e32 v61, v61, v79
	v_mul_f32_e32 v62, v62, v80
	v_mul_f32_e32 v63, v63, v81
	v_mul_f32_e32 v64, v64, v82
	v_mul_f32_e32 v65, v65, v83
	v_mul_f32_e32 v66, v66, v84
	v_mul_f32_e32 v67, v67, v85
	v_mul_f32_e32 v36, v36, v70
	v_mul_f32_e32 v37, v37, v71
	v_mul_f32_e32 v38, v38, v72
	v_mul_f32_e32 v39, v39, v73
	v_mul_f32_e32 v40, v40, v74
	v_mul_f32_e32 v41, v41, v75
	v_mul_f32_e32 v42, v42, v76
	v_mul_f32_e32 v43, v43, v77
	v_mul_f32_e32 v44, v44, v78
	v_mul_f32_e32 v45, v45, v79
	v_mul_f32_e32 v46, v46, v80
	v_mul_f32_e32 v47, v47, v81
	v_mul_f32_e32 v48, v48, v82
	v_mul_f32_e32 v49, v49, v83
	v_mul_f32_e32 v50, v50, v84
	v_mul_f32_e32 v51, v51, v85
	ds_read_b128 v[70:73], v68 offset:128
	ds_read_b128 v[74:77], v68 offset:160
	ds_read_b128 v[78:81], v68 offset:192
	ds_read_b128 v[82:85], v68 offset:224
	ds_write_b32 v34, v52
	ds_write_b32 v34, v53 offset:528
	ds_write_b32 v34, v54 offset:1056
	ds_write_b32 v34, v55 offset:1584
	ds_write_b32 v34, v56 offset:4224
	ds_write_b32 v34, v57 offset:4752
	ds_write_b32 v34, v58 offset:5280
	ds_write_b32 v34, v59 offset:5808
	ds_write_b32 v34, v60 offset:8448
	ds_write_b32 v34, v61 offset:8976
	ds_write_b32 v34, v62 offset:9504
	ds_write_b32 v34, v63 offset:10032
	ds_write_b32 v34, v64 offset:12672
	ds_write_b32 v34, v65 offset:13200
	ds_write_b32 v34, v66 offset:13728
	ds_write_b32 v34, v67 offset:14256
	ds_write_b32 v34, v36 offset:128
	ds_write_b32 v34, v37 offset:656
	ds_write_b32 v34, v38 offset:1184
	ds_write_b32 v34, v39 offset:1712
	ds_write_b32 v34, v40 offset:4352
	ds_write_b32 v34, v41 offset:4880
	ds_write_b32 v34, v42 offset:5408
	ds_write_b32 v34, v43 offset:5936
	ds_write_b32 v34, v44 offset:8576
	ds_write_b32 v34, v45 offset:9104
	ds_write_b32 v34, v46 offset:9632
	ds_write_b32 v34, v47 offset:10160
	ds_write_b32 v34, v48 offset:12800
	ds_write_b32 v34, v49 offset:13328
	ds_write_b32 v34, v50 offset:13856
	ds_write_b32 v34, v51 offset:14384
	s_waitcnt lgkmcnt(0)
	v_mul_f32_e32 v16, v16, v70
	v_mul_f32_e32 v17, v17, v71
	v_mul_f32_e32 v18, v18, v72
	v_mul_f32_e32 v19, v19, v73
	v_mul_f32_e32 v20, v20, v74
	v_mul_f32_e32 v21, v21, v75
	v_mul_f32_e32 v22, v22, v76
	v_mul_f32_e32 v23, v23, v77
	v_mul_f32_e32 v24, v24, v78
	v_mul_f32_e32 v25, v25, v79
	v_mul_f32_e32 v26, v26, v80
	v_mul_f32_e32 v27, v27, v81
	v_mul_f32_e32 v28, v28, v82
	v_mul_f32_e32 v29, v29, v83
	v_mul_f32_e32 v30, v30, v84
	v_mul_f32_e32 v31, v31, v85
	v_mul_f32_e32 v0, v0, v70
	v_mul_f32_e32 v1, v1, v71
	v_mul_f32_e32 v2, v2, v72
	v_mul_f32_e32 v3, v3, v73
	v_mul_f32_e32 v4, v4, v74
	v_mul_f32_e32 v5, v5, v75
	v_mul_f32_e32 v6, v6, v76
	v_mul_f32_e32 v7, v7, v77
	v_mul_f32_e32 v8, v8, v78
	v_mul_f32_e32 v9, v9, v79
	v_mul_f32_e32 v10, v10, v80
	v_mul_f32_e32 v11, v11, v81
	v_mul_f32_e32 v12, v12, v82
	v_mul_f32_e32 v13, v13, v83
	v_mul_f32_e32 v14, v14, v84
	v_mul_f32_e32 v15, v15, v85
	ds_write_b32 v34, v16 offset:16896
	ds_write_b32 v34, v17 offset:17424
	ds_write_b32 v34, v18 offset:17952
	ds_write_b32 v34, v19 offset:18480
	ds_write_b32 v34, v20 offset:21120
	ds_write_b32 v34, v21 offset:21648
	ds_write_b32 v34, v22 offset:22176
	ds_write_b32 v34, v23 offset:22704
	ds_write_b32 v34, v24 offset:25344
	ds_write_b32 v34, v25 offset:25872
	ds_write_b32 v34, v26 offset:26400
	ds_write_b32 v34, v27 offset:26928
	ds_write_b32 v34, v28 offset:29568
	ds_write_b32 v34, v29 offset:30096
	ds_write_b32 v34, v30 offset:30624
	ds_write_b32 v34, v31 offset:31152
	ds_write_b32 v34, v0 offset:17024
	ds_write_b32 v34, v1 offset:17552
	ds_write_b32 v34, v2 offset:18080
	ds_write_b32 v34, v3 offset:18608
	ds_write_b32 v34, v4 offset:21248
	ds_write_b32 v34, v5 offset:21776
	ds_write_b32 v34, v6 offset:22304
	ds_write_b32 v34, v7 offset:22832
	ds_write_b32 v34, v8 offset:25472
	ds_write_b32 v34, v9 offset:26000
	ds_write_b32 v34, v10 offset:26528
	ds_write_b32 v34, v11 offset:27056
	ds_write_b32 v34, v12 offset:29696
	ds_write_b32 v34, v13 offset:30224
	ds_write_b32 v34, v14 offset:30752
	ds_write_b32 v34, v15 offset:31280
	v_mov_b32_e32 v1, v182
	s_waitcnt lgkmcnt(0)
	s_barrier
; DI int tid() { int t = threadIdx.x; asm volatile("" : "+v"(t)); return t; }
; DI void ph_qkv(KP p, int l, char* smem) {
;     ...
;             const int tt = tid(), c8 = tt & 15, n8 = ct * 128 + c8 * 8, head = n8 / 96, w0 = n8 - head * 96;
;             const float qs = 0.10206207261596575f * LOG2E;
; #pragma unroll
;             for (int i = 0; i < 8; ++i) {
;                 const int row = (tt >> 4) + 16 * i, tok = rt * 128 + row;
;                 float4 lo = *(const float4*)(stg + row * 132 + c8 * 8), hi = *(const float4*)(stg + row * 132 + c8 * 8 + 4);
;                 if (w0 >= 64) {
;                     const int c = w0 - 64, pc = c8 * 8 + (c < 16 ? 16 : -16);
;                     const float4 plo = *(const float4*)(stg + row * 132 + pc), phi = *(const float4*)(stg + row * 132 + pc + 4);
;                     rope8(lo, hi, plo, phi, (const float*)(p->ws + OFF_COS) + (size_t)tok * 16, (const float*)(p->ws + OFF_SIN) + (size_t)tok * 16, c);
;                 }
	s_nop 0
	v_lshlrev_b32_e32 v0, 3, v1
	v_and_b32_e32 v25, 0x78, v0
	v_ashrrev_i32_e32 v26, 4, v1
	v_or_b32_e32 v10, s7, v25
	v_and_b32_e32 v9, 8, v0
	v_mul_lo_u32 v0, v26, s82
	v_lshlrev_b32_e32 v1, 2, v25
	v_mul_hi_i32 v2, v10, s87
	v_add3_u32 v8, 0, v0, v1
	v_lshrrev_b32_e32 v11, 31, v2
	v_ashrrev_i32_e32 v12, 4, v2
	ds_read_b128 v[4:7], v8
	ds_read_b128 v[0:3], v8 offset:16
	v_add_u32_e32 v22, v12, v11
	s_movk_i32 s7, 0xffa0
	v_mad_u64_u32 v[16:17], s[8:9], v22, s7, v[10:11]
	s_movk_i32 s7, 0x50
	v_cmp_gt_u32_e32 vcc, s7, v16
	v_and_b32_e32 v10, 0x7ffffff0, v16
	v_add_u32_e32 v18, s6, v26
	v_cndmask_b32_e64 v24, -16, 16, vcc
	v_cmp_eq_u32_e32 vcc, 64, v10
	v_cmp_lt_i32_e64 s[42:43], 63, v16
	v_lshlrev_b32_e32 v34, 2, v9
	v_cndmask_b32_e64 v23, 1.0, -1.0, vcc
	s_and_saveexec_b64 s[16:17], s[42:43]
	s_cbranch_execz .LBB0_214
	v_lshl_add_u32 v8, v24, 2, v8
	v_ashrrev_i32_e32 v19, 31, v18
	ds_read_b128 v[28:31], v8
	ds_read_b128 v[36:39], v8 offset:16
	v_lshlrev_b64 v[8:9], 6, v[18:19]
	v_lshl_add_u64 v[8:9], s[14:15], 0, v[8:9]
	v_lshl_add_u64 v[12:13], v[8:9], 0, v[34:35]
	s_mov_b32 s7, 0x7980000
	s_mov_b64 s[8:9], 0x7980000
	v_add_co_u32_e32 v10, vcc, s7, v12
	v_lshl_add_u64 v[8:9], v[12:13], 0, s[8:9]
	s_nop 0
	v_addc_co_u32_e32 v11, vcc, 0, v13, vcc
	s_mov_b64 s[8:9], 0x7d80000
	s_mov_b32 s7, 0x7d80000
	v_lshl_add_u64 v[14:15], v[12:13], 0, s[8:9]
	v_add_co_u32_e32 v12, vcc, s7, v12
	global_load_dwordx4 v[40:43], v[10:11], off
	s_nop 0
	global_load_dwordx4 v[8:11], v[8:9], off offset:16
	v_addc_co_u32_e32 v13, vcc, 0, v13, vcc
	global_load_dwordx4 v[44:47], v[12:13], off
	s_nop 0
	global_load_dwordx4 v[12:15], v[14:15], off offset:16
	s_waitcnt lgkmcnt(1)
	v_mul_f32_e32 v17, v23, v28
	v_mul_f32_e32 v29, v23, v29
	v_mov_b32_e32 v28, v5
	s_waitcnt vmcnt(3)
	v_mul_f32_e32 v4, v4, v40
	v_mul_f32_e32 v6, v6, v42
	s_waitcnt vmcnt(2)
	v_mul_f32_e32 v0, v0, v8
	s_waitcnt vmcnt(1)
	v_mul_f32_e32 v20, v17, v44
	v_mov_b32_e32 v44, v41
	v_pk_mul_f32 v[28:29], v[28:29], v[44:45]
	v_mul_f32_e32 v17, v23, v30
	v_mov_b32_e32 v5, v28
	v_mov_b32_e32 v21, v29
	v_pk_add_f32 v[4:5], v[4:5], v[20:21]
	v_mul_f32_e32 v20, v17, v46
	v_mul_f32_e32 v29, v23, v31
	v_mov_b32_e32 v28, v7
	v_mov_b32_e32 v46, v43
	v_pk_mul_f32 v[28:29], v[28:29], v[46:47]
	s_waitcnt lgkmcnt(0)
	v_mul_f32_e32 v8, v23, v36
	v_mov_b32_e32 v7, v28
	v_mov_b32_e32 v21, v29
	v_pk_add_f32 v[6:7], v[6:7], v[20:21]
	s_waitcnt vmcnt(0)
	v_mul_f32_e32 v8, v8, v12
	v_mul_f32_e32 v21, v23, v37
	v_mov_b32_e32 v20, v1
	v_mov_b32_e32 v12, v9
	v_pk_mul_f32 v[12:13], v[20:21], v[12:13]
	v_mul_f32_e32 v2, v2, v10
	v_mov_b32_e32 v1, v12
	v_mov_b32_e32 v9, v13
	v_pk_add_f32 v[0:1], v[0:1], v[8:9]
	v_mul_f32_e32 v8, v23, v38
	v_mul_f32_e32 v8, v8, v14
	v_mul_f32_e32 v13, v23, v39
	v_mov_b32_e32 v12, v3
	v_mov_b32_e32 v14, v11
	v_pk_mul_f32 v[10:11], v[12:13], v[14:15]
	s_nop 0
	v_mov_b32_e32 v3, v10
	v_mov_b32_e32 v9, v11
	v_pk_add_f32 v[2:3], v[2:3], v[8:9]

; DI unsigned xb_add(unsigned* p, unsigned v) { return __hip_atomic_fetch_add(p, v, __ATOMIC_RELAXED, __HIP_MEMORY_SCOPE_AGENT); }
; DI void xcd_barrier(const XcdBarrier& b) {
;     asm volatile("s_waitcnt vmcnt(0)" ::: "memory");
;     __syncthreads();
;     if (threadIdx.x == 0) {
;         unsigned* bar = b.bar;
;         __builtin_amdgcn_s_waitcnt(0);
;         unsigned nloc = b.st[0], nx = b.st[1];
;         if (nloc == 0u) { xcd_barrier_complete(bar, b.x, nloc, nx); b.st[0] = nloc; b.st[1] = nx; }
;         const unsigned old = xb_add(&bar[XB_XSUB(b.x)], 1u);
;         const unsigned gen = old / nloc;
; __global__ void __launch_bounds__(256, 2) mk(Params p_unused, int lo, int hi) {
;     ...
;         if (ph + 1 < hi) { if (ph == 0) grid.sync(); else if (ph != 1) xcd_barrier(xbar); }
.LBB0_1444:
	s_mov_b64 s[0:1], 0
	s_cmp_lg_u32 s64, 1
	s_mov_b64 s[14:15], 0
	s_cbranch_scc0 .LBB0_1457
	s_waitcnt vmcnt(0)
	s_waitcnt lgkmcnt(0)
	s_barrier
	s_mov_b64 s[14:15], exec
	v_readlane_b32 s6, v231, 4
	v_readlane_b32 s7, v231, 5
	s_and_b64 s[6:7], s[14:15], s[6:7]
	s_mov_b64 exec, s[6:7]
	s_cbranch_execz .LBB0_1523
	v_readlane_b32 s2, v230, 59
	s_waitcnt vmcnt(0) expcnt(0) lgkmcnt(0)
	s_nop 0
	v_mov_b32_e32 v0, s2
	ds_read_b32 v2, v0
	v_readlane_b32 s2, v230, 60
	s_waitcnt lgkmcnt(0)
	v_cmp_ne_u32_e32 vcc, 0, v2
	v_mov_b32_e32 v0, s2
	ds_read_b32 v0, v0
	s_cbranch_vccnz .LBB0_1477
	s_mov_b32 s2, 1
	s_branch .LBB0_1450
